# 7.11 completion: MLA loop laid out so the loop-back barrier falls through into the K-fragment reads (entry head placed in front of the loop tail)
# speedup vs baseline: 1.0047x; 1.0016x over previous
.LBB0_557:
	s_cmpk_lg_i32 s4, 0x1080
	s_cselect_b64 s[2:3], -1, 0
	s_cmpk_eq_i32 s4, 0x1080
	s_cbranch_scc1 .LBB0_559
	v_add_u32_e32 v10, s4, v137
	v_add_u32_e32 v18, s4, v117
	v_add_u32_e32 v34, s4, v115
	v_ashrrev_i32_e32 v11, 31, v10
	v_ashrrev_i32_e32 v19, 31, v18
	v_ashrrev_i32_e32 v35, 31, v34
	v_lshlrev_b64 v[14:15], 11, v[10:11]
	v_lshlrev_b64 v[22:23], 11, v[18:19]
	v_lshlrev_b64 v[34:35], 6, v[34:35]
	v_lshl_add_u64 v[10:11], v[118:119], 0, v[14:15]
	v_lshl_add_u64 v[14:15], v[120:121], 0, v[14:15]
	v_lshl_add_u64 v[18:19], v[118:119], 0, v[22:23]
	v_lshl_add_u64 v[22:23], v[120:121], 0, v[22:23]
	v_lshl_add_u64 v[34:35], v[122:123], 0, v[34:35]
	global_load_dwordx4 v[10:13], v[10:11], off
	s_nop 0
	global_load_dwordx4 v[14:17], v[14:15], off
	s_nop 0
	global_load_dwordx4 v[18:21], v[18:19], off
	s_nop 0
	global_load_dwordx4 v[22:25], v[22:23], off
	s_nop 0
	global_load_dwordx4 v[34:37], v[34:35], off
	s_branch .LBB0_559

.Lmla_rot_nopf:
	s_cmpk_lg_i32 s4, 0x1100
	s_barrier
	s_cbranch_scc0 .LBB0_554
.LBB0_559:
	s_and_b32 s5, s4, 0x80
	v_or_b32_e32 v142, s5, v125
	v_mad_u32_u24 v143, v142, s12, v0
	ds_read_b128 v[78:81], v143
	ds_read_b128 v[82:85], v143 offset:64
	ds_read_b128 v[86:89], v143 offset:128
	ds_read_b128 v[94:97], v143 offset:3328
	ds_read_b128 v[98:101], v143 offset:3392
	ds_read_b128 v[144:147], v143 offset:3456
	s_setprio 1
	s_waitcnt lgkmcnt(5)
	v_mfma_f32_16x16x32_bf16 v[90:93], v[78:81], v[2:5], 0
	v_mfma_f32_16x16x32_bf16 v[78:81], v[78:81], v[26:29], 0
	s_waitcnt lgkmcnt(4)
	v_mfma_f32_16x16x32_bf16 v[90:93], v[82:85], v[6:9], v[90:93]
	v_mfma_f32_16x16x32_bf16 v[78:81], v[82:85], v[30:33], v[78:81]
	s_waitcnt lgkmcnt(3)
	v_mfma_f32_16x16x32_bf16 v[106:109], v[86:89], v[38:41], v[90:93]
	v_mfma_f32_16x16x32_bf16 v[90:93], v[86:89], v[42:45], v[78:81]
	s_waitcnt lgkmcnt(2)
	v_mfma_f32_16x16x32_bf16 v[78:81], v[94:97], v[2:5], 0
	v_mfma_f32_16x16x32_bf16 v[82:85], v[94:97], v[26:29], 0
	s_waitcnt lgkmcnt(1)
	v_mfma_f32_16x16x32_bf16 v[78:81], v[98:101], v[6:9], v[78:81]
	v_mfma_f32_16x16x32_bf16 v[82:85], v[98:101], v[30:33], v[82:85]
	s_waitcnt lgkmcnt(0)
	v_mfma_f32_16x16x32_bf16 v[102:105], v[144:147], v[38:41], v[78:81]
	v_mfma_f32_16x16x32_bf16 v[82:85], v[144:147], v[42:45], v[82:85]
	s_setprio 0
	s_nop 2
	ds_read_b128 v[78:81], v143 offset:6656
	ds_read_b128 v[86:89], v143 offset:6720
	ds_read_b128 v[94:97], v143 offset:6784
	ds_read_b128 v[144:147], v143 offset:9984
	ds_read_b128 v[148:151], v143 offset:10048
	ds_read_b128 v[152:155], v143 offset:10112
	s_setprio 1
	s_waitcnt lgkmcnt(5)
	v_mfma_f32_16x16x32_bf16 v[98:101], v[78:81], v[2:5], 0
	v_mfma_f32_16x16x32_bf16 v[78:81], v[78:81], v[26:29], 0
	s_waitcnt lgkmcnt(4)
	v_mfma_f32_16x16x32_bf16 v[98:101], v[86:89], v[6:9], v[98:101]
	v_mfma_f32_16x16x32_bf16 v[78:81], v[86:89], v[30:33], v[78:81]
	s_waitcnt lgkmcnt(3)
	v_mfma_f32_16x16x32_bf16 v[98:101], v[94:97], v[38:41], v[98:101]
	v_mfma_f32_16x16x32_bf16 v[86:89], v[94:97], v[42:45], v[78:81]
	s_waitcnt lgkmcnt(2)
	v_mfma_f32_16x16x32_bf16 v[78:81], v[144:147], v[2:5], 0
	v_mfma_f32_16x16x32_bf16 v[94:97], v[144:147], v[26:29], 0
	s_waitcnt lgkmcnt(1)
	v_mfma_f32_16x16x32_bf16 v[78:81], v[148:151], v[6:9], v[78:81]
	v_mfma_f32_16x16x32_bf16 v[144:147], v[148:151], v[30:33], v[94:97]
	s_waitcnt lgkmcnt(0)
	v_mfma_f32_16x16x32_bf16 v[94:97], v[152:155], v[38:41], v[78:81]
	v_mfma_f32_16x16x32_bf16 v[78:81], v[152:155], v[42:45], v[144:147]
	s_setprio 0
	v_max3_f32 v143, v106, s18, v107
	v_max3_f32 v143, v143, v108, v109
	v_max3_f32 v143, v143, v102, v103
	v_max3_f32 v143, v143, v104, v105
	v_max3_f32 v143, v143, v98, v99
	v_max3_f32 v143, v143, v100, v101
	v_max3_f32 v143, v143, v94, v95
	v_max3_f32 v143, v143, v96, v97
	v_mul_f32_e32 v143, 0x3e16c740, v143
	v_mov_b32_e32 v144, v143
	s_nop 1
	v_permlane16_swap_b32_e32 v144, v143
	v_max_f32_e32 v143, v143, v144
	v_mov_b32_e32 v144, v143
	s_nop 1
	v_permlane32_swap_b32_e32 v144, v143
	v_max_f32_e32 v143, v143, v144
	v_add_f32_e32 v144, 0x41000000, v139
	v_cmp_gt_f32_e32 vcc, v143, v144
	s_cbranch_vccz .LBB0_561
	v_max_f32_e32 v143, v143, v143
	v_max_f32_e32 v144, v139, v139
	v_max_f32_e32 v143, v144, v143
	v_sub_f32_e32 v139, v139, v143
	v_exp_f32_e32 v144, v139
	v_mov_b32_e32 v139, v143
	v_mul_f32_e32 v141, v141, v144
	v_pk_mul_f32 v[76:77], v[76:77], v[144:145] op_sel_hi:[1,0]
	v_pk_mul_f32 v[74:75], v[74:75], v[144:145] op_sel_hi:[1,0]
	v_pk_mul_f32 v[72:73], v[72:73], v[144:145] op_sel_hi:[1,0]
	v_pk_mul_f32 v[70:71], v[70:71], v[144:145] op_sel_hi:[1,0]
	v_pk_mul_f32 v[68:69], v[68:69], v[144:145] op_sel_hi:[1,0]
	v_pk_mul_f32 v[66:67], v[66:67], v[144:145] op_sel_hi:[1,0]
	v_pk_mul_f32 v[64:65], v[64:65], v[144:145] op_sel_hi:[1,0]
	v_pk_mul_f32 v[62:63], v[62:63], v[144:145] op_sel_hi:[1,0]
